# FFN1-in phase: workgroups start their tile stream staggered by (bx&3) x ~0.9us so the aligned epilogue store bursts of the 256 CUs do not coincide
# speedup vs baseline: 1.0019x; 1.0019x over previous
.LBB0_397:
	s_lshl_b32 s4, s4, 5
	s_and_b32 s8, s4, 0x60
	s_add_i32 m0, s28, 0x18000
	v_lshl_add_u64 v[8:9], v[8:9], 0, s[96:97]
	s_lshl_b32 s6, s5, 6
	s_lshl_b32 s7, s5, 13
	s_lshl_b32 s9, s8, 7
	s_waitcnt vmcnt(2)
	s_barrier
	global_load_lds_dwordx4 v[8:9], off
	v_lshl_add_u64 v[6:7], v[6:7], 0, s[96:97]
	s_add_i32 m0, s28, 0x1a000
	s_add_i32 s34, s28, 0x8000
	s_add_i32 s35, s28, 0xa000
	global_load_lds_dwordx4 v[6:7], off
	v_lshl_add_u64 v[2:3], v[2:3], 0, s[96:97]
	s_mov_b32 m0, s34
	s_add_u32 s4, s20, 0x40080
	global_load_lds_dwordx4 v[2:3], off
	v_lshl_add_u64 v[2:3], v[4:5], 0, s[96:97]
	s_mov_b32 m0, s35
	s_addc_u32 s5, s21, 0
	global_load_lds_dwordx4 v[2:3], off
	s_add_i32 m0, s28, 0x1c000
	v_lshl_add_u64 v[2:3], s[4:5], 0, v[154:155]
	global_load_lds_dwordx4 v[2:3], off
	v_lshl_add_u64 v[2:3], s[4:5], 0, v[150:151]
	s_add_i32 m0, s28, 0x1e000
	v_lshlrev_b32_e32 v5, 2, v11
	global_load_lds_dwordx4 v[2:3], off
	v_bfe_u32 v3, v11, 4, 2
	v_and_b32_e32 v2, 15, v11
	v_lshlrev_b32_e32 v4, 4, v3
	v_lshl_or_b32 v4, v2, 6, v4
	v_or_b32_e32 v158, s6, v2
	v_lshlrev_b32_e32 v2, 2, v3
	v_lshl_or_b32 v175, v3, 3, s8
	v_lshlrev_b32_e32 v3, 14, v14
	v_and_b32_e32 v5, 32, v5
	v_and_b32_e32 v3, 0xffff8000, v3
	v_bitop3_b32 v6, v4, s7, v5 bitop3:0xde
	v_bitop3_b32 v173, v4, s9, v5 bitop3:0xde
	v_lshl_add_u32 v3, v13, 11, v3
	v_and_b32_e32 v4, 1, v14
	v_lshl_or_b32 v3, v4, 6, v3
	v_lshl_add_u32 v166, v15, 1, v3
	v_lshlrev_b32_e32 v3, 14, v0
	v_and_b32_e32 v3, 0xffff8000, v3
	s_waitcnt vmcnt(6)
	s_cmpk_lt_u32 s1, 0x100
	v_lshl_add_u32 v3, v10, 11, v3
	v_and_b32_e32 v0, 1, v0
	s_sext_i32_i16 s17, s0
	s_cselect_b64 s[4:5], -1, 0
	s_ashr_i32 s0, s6, 31
	v_lshl_or_b32 v0, v0, 6, v3
	v_mov_b32_e32 v159, s0
	v_or_b32_e32 v160, 16, v158
	v_mov_b32_e32 v161, s0
	v_or_b32_e32 v162, 32, v158
	v_mov_b32_e32 v163, s0
	v_or_b32_e32 v164, 48, v158
	v_mov_b32_e32 v165, s0
	v_mov_b32_e32 v167, v1
	v_lshl_add_u32 v168, v12, 1, v0
	v_mov_b32_e32 v169, v1
	s_mov_b32 s36, 0
	v_add_u32_e32 v185, 0, v6
	v_lshlrev_b32_e32 v0, 2, v2
	s_barrier
	s_and_b32 s98, s13, 3
.Lstag_a:
	s_cmp_eq_u32 s98, 0
	s_cbranch_scc1 .Lstag_a_done
	s_sleep 32
	s_sub_u32 s98, s98, 1
	s_branch .Lstag_a
.Lstag_a_done:
	s_branch .LBB0_400
.LBB0_398:
	s_mov_b64 s[16:17], 0
